# sgu_spatial: row-statistics loads and Ws-tile loads each issued together with counted waits (was load + full wait x4 per chunk / per group), on top of v40
# baseline (speedup 1.0000x reference)
; __device__ __forceinline__ void sgu_spatial(CP pp, LAS unsigned char* lds) {
;     ...
;         for (int it = 0; it < 4; ++it) {
;             const int id = it * NTHR + tid, pp_ = id >> 4;
;             const f32x4 t = *(const f32x4*)((const float*)(STAT + (size_t)r0 * 32) + (size_t)id * 4);
;             float sm = t[0] + t[2], sq = t[1] + t[3];
; #pragma unroll
;             for (int o = 1; o < 16; o <<= 1) { sm += __shfl_xor(sm, o); sq += __shfl_xor(sq, o); }
;             if ((id & 15) == 0) { const float mean = sm * (1.0f / DSGU), var = sq * (1.0f / DSGU) - mean * mean; MU[pp_] = mean; RS[pp_] = 1.0f / sqrtf(fmaxf(var, 0.f) + EPS); }
;         }
.LBB0_65:
	s_lshl_b32 s20, s2, 7
	s_ashr_i32 s21, s20, 31
	s_lshl_b64 s[4:5], s[20:21], 8
	s_add_u32 s22, s64, s4
	s_addc_u32 s23, s65, s5
	v_lshl_add_u64 v[0:1], s[22:23], 0, v[82:83]
	global_load_dwordx4 v[0:3], v[0:1], off
	v_lshl_add_u64 v[76:77], s[22:23], 0, v[84:85]
	global_load_dwordx4 v[76:79], v[76:77], off
	v_lshl_add_u64 v[72:73], s[22:23], 0, v[86:87]
	global_load_dwordx4 v[72:75], v[72:73], off
	v_lshl_add_u64 v[56:57], s[22:23], 0, v[88:89]
	global_load_dwordx4 v[56:59], v[56:57], off
	s_waitcnt vmcnt(3)
	v_add_f32_e32 v0, v0, v2
	v_add_f32_e32 v1, v1, v3
	ds_bpermute_b32 v2, v192, v0
	ds_bpermute_b32 v3, v192, v1
	s_waitcnt lgkmcnt(1)
	v_add_f32_e32 v0, v0, v2
	s_waitcnt lgkmcnt(0)
	v_add_f32_e32 v1, v1, v3
	ds_bpermute_b32 v2, v193, v0
	ds_bpermute_b32 v3, v193, v1
	s_waitcnt lgkmcnt(1)
	v_add_f32_e32 v0, v0, v2
	s_waitcnt lgkmcnt(0)
	v_add_f32_e32 v1, v1, v3
	ds_bpermute_b32 v2, v194, v0
	ds_bpermute_b32 v3, v194, v1
	s_waitcnt lgkmcnt(1)
	v_add_f32_e32 v0, v0, v2
	s_waitcnt lgkmcnt(0)
	v_add_f32_e32 v1, v1, v3
	ds_bpermute_b32 v2, v195, v0
	ds_bpermute_b32 v3, v195, v1
	s_and_saveexec_b64 s[74:75], s[8:9]
	s_cbranch_execz .LBB0_67
	s_waitcnt lgkmcnt(1)
	v_add_f32_e32 v0, v0, v2
	v_mul_f32_e32 v0, 0x3a000000, v0
	s_waitcnt lgkmcnt(0)
	v_add_f32_e32 v1, v1, v3
	v_mul_f32_e32 v2, v0, v0
	s_mov_b32 s4, 0x3a000000
	v_fma_f32 v1, v1, s4, -v2
	v_max_f32_e32 v1, 0, v1
	v_add_f32_e32 v1, 0x358637bd, v1
	v_mul_f32_e32 v2, 0x4f800000, v1
	v_cmp_gt_f32_e32 vcc, s44, v1
	ds_write_b32 v243, v0
	s_nop 0
	v_cndmask_b32_e32 v1, v1, v2, vcc
	v_sqrt_f32_e32 v2, v1
	s_nop 0
	v_add_u32_e32 v3, -1, v2
	v_fma_f32 v4, -v3, v2, v1
	v_cmp_ge_f32_e64 s[10:11], 0, v4
	v_add_u32_e32 v4, 1, v2
	s_nop 0
	v_cndmask_b32_e64 v3, v2, v3, s[10:11]
	v_fma_f32 v2, -v4, v2, v1
	v_cmp_lt_f32_e64 s[10:11], 0, v2
	s_nop 1
	v_cndmask_b32_e64 v2, v3, v4, s[10:11]
	v_mul_f32_e32 v3, 0x37800000, v2
	v_cndmask_b32_e32 v2, v2, v3, vcc
	v_cmp_class_f32_e32 vcc, v1, v167
	s_nop 1
	v_cndmask_b32_e32 v1, v2, v1, vcc
	v_div_scale_f32 v2, s[4:5], v1, v1, 1.0
	v_rcp_f32_e32 v3, v2
	s_nop 0
	v_fma_f32 v0, -v2, v3, 1.0
	v_fmac_f32_e32 v3, v0, v3
	v_div_scale_f32 v0, vcc, 1.0, v1, 1.0
	v_mul_f32_e32 v4, v0, v3
	v_fma_f32 v5, -v2, v4, v0
	v_fmac_f32_e32 v4, v5, v3
	v_fma_f32 v0, -v2, v4, v0
	v_div_fmas_f32 v0, v0, v3, v4
	v_div_fixup_f32 v0, v0, v1, 1.0
	ds_write_b32 v169, v0
.LBB0_67:
	s_or_b64 exec, exec, s[74:75]
	s_waitcnt vmcnt(2)
	s_waitcnt lgkmcnt(0)
	v_mov_b32_e32 v0, v76
	v_mov_b32_e32 v1, v77
	v_mov_b32_e32 v2, v78
	v_mov_b32_e32 v3, v79
	s_nop 0
	v_add_f32_e32 v0, v0, v2
	v_add_f32_e32 v1, v1, v3
	ds_bpermute_b32 v2, v192, v0
	ds_bpermute_b32 v3, v192, v1
	s_waitcnt lgkmcnt(1)
	v_add_f32_e32 v0, v0, v2
	s_waitcnt lgkmcnt(0)
	v_add_f32_e32 v1, v1, v3
	ds_bpermute_b32 v2, v193, v0
	ds_bpermute_b32 v3, v193, v1
	s_waitcnt lgkmcnt(1)
	v_add_f32_e32 v0, v0, v2
	s_waitcnt lgkmcnt(0)
	v_add_f32_e32 v1, v1, v3
	ds_bpermute_b32 v2, v194, v0
	ds_bpermute_b32 v3, v194, v1
	s_waitcnt lgkmcnt(1)
	v_add_f32_e32 v0, v0, v2
	s_waitcnt lgkmcnt(0)
	v_add_f32_e32 v1, v1, v3
	ds_bpermute_b32 v2, v195, v0
	ds_bpermute_b32 v3, v195, v1
	s_and_saveexec_b64 s[74:75], s[8:9]
	s_cbranch_execz .LBB0_69
	s_waitcnt lgkmcnt(1)
	v_add_f32_e32 v0, v0, v2
	v_mul_f32_e32 v0, 0x3a000000, v0
	s_waitcnt lgkmcnt(0)
	v_add_f32_e32 v1, v1, v3
	v_mul_f32_e32 v2, v0, v0
	s_mov_b32 s4, 0x3a000000
	v_fma_f32 v1, v1, s4, -v2
	v_max_f32_e32 v1, 0, v1
	v_add_f32_e32 v1, 0x358637bd, v1
	v_mul_f32_e32 v2, 0x4f800000, v1
	v_cmp_gt_f32_e32 vcc, s44, v1
	ds_write_b32 v173, v0
	s_nop 0
	v_cndmask_b32_e32 v1, v1, v2, vcc
	v_sqrt_f32_e32 v2, v1
	s_nop 0
	v_add_u32_e32 v3, -1, v2
	v_fma_f32 v4, -v3, v2, v1
	v_cmp_ge_f32_e64 s[10:11], 0, v4
	v_add_u32_e32 v4, 1, v2
	s_nop 0
	v_cndmask_b32_e64 v3, v2, v3, s[10:11]
	v_fma_f32 v2, -v4, v2, v1
	v_cmp_lt_f32_e64 s[10:11], 0, v2
	s_nop 1
	v_cndmask_b32_e64 v2, v3, v4, s[10:11]
	v_mul_f32_e32 v3, 0x37800000, v2
	v_cndmask_b32_e32 v2, v2, v3, vcc
	v_cmp_class_f32_e32 vcc, v1, v167
	s_nop 1
	v_cndmask_b32_e32 v1, v2, v1, vcc
	v_div_scale_f32 v2, s[4:5], v1, v1, 1.0
	v_rcp_f32_e32 v3, v2
	s_nop 0
	v_fma_f32 v0, -v2, v3, 1.0
	v_fmac_f32_e32 v3, v0, v3
	v_div_scale_f32 v0, vcc, 1.0, v1, 1.0
	v_mul_f32_e32 v4, v0, v3
	v_fma_f32 v5, -v2, v4, v0
	v_fmac_f32_e32 v4, v5, v3
	v_fma_f32 v0, -v2, v4, v0
	v_div_fmas_f32 v0, v0, v3, v4
	v_div_fixup_f32 v0, v0, v1, 1.0
	ds_write_b32 v254, v0
; __device__ __forceinline__ void sgu_spatial(CP pp, LAS unsigned char* lds) {
;     ...
;         for (int it = 0; it < 4; ++it) {
;             const int id = it * NTHR + tid, pp_ = id >> 4;
;             const f32x4 t = *(const f32x4*)((const float*)(STAT + (size_t)r0 * 32) + (size_t)id * 4);
;             float sm = t[0] + t[2], sq = t[1] + t[3];
; #pragma unroll
;             for (int o = 1; o < 16; o <<= 1) { sm += __shfl_xor(sm, o); sq += __shfl_xor(sq, o); }
;             if ((id & 15) == 0) { const float mean = sm * (1.0f / DSGU), var = sq * (1.0f / DSGU) - mean * mean; MU[pp_] = mean; RS[pp_] = 1.0f / sqrtf(fmaxf(var, 0.f) + EPS); }
;         }
.LBB0_69:
	s_or_b64 exec, exec, s[74:75]
	s_waitcnt vmcnt(1)
	s_waitcnt lgkmcnt(0)
	v_mov_b32_e32 v0, v72
	v_mov_b32_e32 v1, v73
	v_mov_b32_e32 v2, v74
	v_mov_b32_e32 v3, v75
	s_nop 0
	v_add_f32_e32 v0, v0, v2
	v_add_f32_e32 v1, v1, v3
	ds_bpermute_b32 v2, v192, v0
	ds_bpermute_b32 v3, v192, v1
	s_waitcnt lgkmcnt(1)
	v_add_f32_e32 v0, v0, v2
	s_waitcnt lgkmcnt(0)
	v_add_f32_e32 v1, v1, v3
	ds_bpermute_b32 v2, v193, v0
	ds_bpermute_b32 v3, v193, v1
	s_waitcnt lgkmcnt(1)
	v_add_f32_e32 v0, v0, v2
	s_waitcnt lgkmcnt(0)
	v_add_f32_e32 v1, v1, v3
	ds_bpermute_b32 v2, v194, v0
	ds_bpermute_b32 v3, v194, v1
	s_waitcnt lgkmcnt(1)
	v_add_f32_e32 v0, v0, v2
	s_waitcnt lgkmcnt(0)
	v_add_f32_e32 v1, v1, v3
	ds_bpermute_b32 v2, v195, v0
	ds_bpermute_b32 v3, v195, v1
	s_and_saveexec_b64 s[74:75], s[8:9]
	s_cbranch_execz .LBB0_71
	s_waitcnt lgkmcnt(1)
	v_add_f32_e32 v0, v0, v2
	v_mul_f32_e32 v0, 0x3a000000, v0
	s_waitcnt lgkmcnt(0)
	v_add_f32_e32 v1, v1, v3
	v_mul_f32_e32 v2, v0, v0
	s_mov_b32 s4, 0x3a000000
	v_fma_f32 v1, v1, s4, -v2
	v_max_f32_e32 v1, 0, v1
	v_add_f32_e32 v1, 0x358637bd, v1
	v_mul_f32_e32 v2, 0x4f800000, v1
	v_cmp_gt_f32_e32 vcc, s44, v1
	ds_write_b32 v200, v0
	s_nop 0
	v_cndmask_b32_e32 v1, v1, v2, vcc
	v_sqrt_f32_e32 v2, v1
	s_nop 0
	v_add_u32_e32 v3, -1, v2
	v_fma_f32 v4, -v3, v2, v1
	v_cmp_ge_f32_e64 s[10:11], 0, v4
	v_add_u32_e32 v4, 1, v2
	s_nop 0
	v_cndmask_b32_e64 v3, v2, v3, s[10:11]
	v_fma_f32 v2, -v4, v2, v1
	v_cmp_lt_f32_e64 s[10:11], 0, v2
	s_nop 1
	v_cndmask_b32_e64 v2, v3, v4, s[10:11]
	v_mul_f32_e32 v3, 0x37800000, v2
	v_cndmask_b32_e32 v2, v2, v3, vcc
	v_cmp_class_f32_e32 vcc, v1, v167
	s_nop 1
	v_cndmask_b32_e32 v1, v2, v1, vcc
	v_div_scale_f32 v2, s[4:5], v1, v1, 1.0
	v_rcp_f32_e32 v3, v2
	s_nop 0
	v_fma_f32 v0, -v2, v3, 1.0
	v_fmac_f32_e32 v3, v0, v3
	v_div_scale_f32 v0, vcc, 1.0, v1, 1.0
	v_mul_f32_e32 v4, v0, v3
	v_fma_f32 v5, -v2, v4, v0
	v_fmac_f32_e32 v4, v5, v3
	v_fma_f32 v0, -v2, v4, v0
	v_div_fmas_f32 v0, v0, v3, v4
	v_div_fixup_f32 v0, v0, v1, 1.0
	ds_write_b32 v201, v0
.LBB0_71:
	s_or_b64 exec, exec, s[74:75]
	s_waitcnt vmcnt(0)
	s_waitcnt lgkmcnt(0)
	v_mov_b32_e32 v0, v56
	v_mov_b32_e32 v1, v57
	v_mov_b32_e32 v2, v58
	v_mov_b32_e32 v3, v59
	s_nop 0
	v_add_f32_e32 v0, v0, v2
	v_add_f32_e32 v1, v1, v3
	ds_bpermute_b32 v2, v192, v0
	ds_bpermute_b32 v3, v192, v1
	s_waitcnt lgkmcnt(1)
	v_add_f32_e32 v0, v0, v2
	s_waitcnt lgkmcnt(0)
	v_add_f32_e32 v1, v1, v3
	ds_bpermute_b32 v2, v193, v0
	ds_bpermute_b32 v3, v193, v1
	s_waitcnt lgkmcnt(1)
	v_add_f32_e32 v0, v0, v2
	s_waitcnt lgkmcnt(0)
	v_add_f32_e32 v1, v1, v3
	ds_bpermute_b32 v2, v194, v0
	ds_bpermute_b32 v3, v194, v1
	s_waitcnt lgkmcnt(1)
	v_add_f32_e32 v0, v0, v2
	s_waitcnt lgkmcnt(0)
	v_add_f32_e32 v1, v1, v3
	ds_bpermute_b32 v2, v195, v0
	ds_bpermute_b32 v3, v195, v1
	s_and_saveexec_b64 s[22:23], s[8:9]
	s_cbranch_execz .LBB0_73
	s_waitcnt lgkmcnt(1)
	v_add_f32_e32 v0, v0, v2
	v_mul_f32_e32 v0, 0x3a000000, v0
	s_waitcnt lgkmcnt(0)
	v_add_f32_e32 v1, v1, v3
	v_mul_f32_e32 v2, v0, v0
	s_mov_b32 s4, 0x3a000000
	v_fma_f32 v1, v1, s4, -v2
	v_max_f32_e32 v1, 0, v1
	v_add_f32_e32 v1, 0x358637bd, v1
	v_mul_f32_e32 v2, 0x4f800000, v1
	v_cmp_gt_f32_e32 vcc, s44, v1
	ds_write_b32 v202, v0
	s_nop 0
	v_cndmask_b32_e32 v1, v1, v2, vcc
	v_sqrt_f32_e32 v2, v1
	s_nop 0
	v_add_u32_e32 v3, -1, v2
	v_fma_f32 v4, -v3, v2, v1
	v_cmp_ge_f32_e64 s[10:11], 0, v4
	v_add_u32_e32 v4, 1, v2
	s_nop 0
	v_cndmask_b32_e64 v3, v2, v3, s[10:11]
	v_fma_f32 v2, -v4, v2, v1
	v_cmp_lt_f32_e64 s[10:11], 0, v2
	s_nop 1
	v_cndmask_b32_e64 v2, v3, v4, s[10:11]
	v_mul_f32_e32 v3, 0x37800000, v2
	v_cndmask_b32_e32 v2, v2, v3, vcc
	v_cmp_class_f32_e32 vcc, v1, v167
	s_nop 1
	v_cndmask_b32_e32 v1, v2, v1, vcc
	v_div_scale_f32 v2, s[4:5], v1, v1, 1.0
	v_rcp_f32_e32 v3, v2
	s_nop 0
	v_fma_f32 v0, -v2, v3, 1.0
	v_fmac_f32_e32 v3, v0, v3
	v_div_scale_f32 v0, vcc, 1.0, v1, 1.0
	v_mul_f32_e32 v4, v0, v3
	v_fma_f32 v5, -v2, v4, v0
	v_fmac_f32_e32 v4, v5, v3
	v_fma_f32 v0, -v2, v4, v0
	v_div_fmas_f32 v0, v0, v3, v4
	v_div_fixup_f32 v0, v0, v1, 1.0
	ds_write_b32 v203, v0
